# cprep item loop: loop-top vmcnt(0) (which also waited for the previous item's 32 short stores) moved to loop entry; prefetched loads are already waited at the loop tail
# baseline (speedup 1.0000x reference)
.LBB0_633:
	v_readlane_b32 s6, v253, 11
	v_readlane_b32 s7, v253, 12
	s_waitcnt lgkmcnt(0)
	v_mov_b32_e32 v0, v201
	s_andn2_b64 vcc, exec, s[6:7]
	s_cbranch_vccnz .LBB0_676
	v_readlane_b32 s6, v253, 55
	v_readlane_b32 s7, v253, 56
	s_load_dwordx2 s[6:7], s[6:7], 0x160
	s_waitcnt vmcnt(13)
	v_ashrrev_i32_e32 v2, 4, v0
	v_readlane_b32 s49, v253, 16
	v_readlane_b32 s8, v253, 18
	v_lshlrev_b32_e32 v0, 2, v0
	s_waitcnt lgkmcnt(0)
	s_add_u32 s50, s6, 0x6c48000
	s_addc_u32 s51, s7, 0
	v_add_u32_e32 v2, s49, v2
	s_add_u32 s52, s6, 0x1cb48000
	v_ashrrev_i32_e32 v3, 31, v2
	s_addc_u32 s53, s7, 0
	v_lshlrev_b64 v[2:3], 9, v[2:3]
	s_add_u32 s54, s6, 0x9048000
	s_addc_u32 s55, s7, 0
	v_or_b32_e32 v2, s8, v2
	s_add_u32 s56, s6, 0x18348000
	v_and_or_b32 v2, v0, 60, v2
	s_addc_u32 s57, s7, 0
	v_lshlrev_b64 v[4:5], 1, v[2:3]
	s_waitcnt vmcnt(12)
	v_lshl_add_u64 v[6:7], s[56:57], 0, v[4:5]
	v_add_co_u32_e32 v8, vcc, s2, v6
	v_lshl_add_u64 v[10:11], s[52:53], 0, v[4:5]
	s_nop 0
	v_addc_co_u32_e32 v9, vcc, 0, v7, vcc
	v_add_co_u32_e32 v12, vcc, s2, v10
	s_add_u32 s58, s6, 0x15f48000
	s_nop 0
	v_addc_co_u32_e32 v13, vcc, 0, v11, vcc
	global_load_dwordx2 v[60:61], v[6:7], off
	global_load_dwordx2 v[58:59], v[8:9], off
	global_load_dwordx2 v[70:71], v[10:11], off
	global_load_dwordx2 v[72:73], v[12:13], off
	v_lshl_add_u64 v[6:7], s[54:55], 0, v[4:5]
	s_addc_u32 s59, s7, 0
	v_add_co_u32_e32 v8, vcc, s2, v6
	s_add_u32 s60, s6, 0x1a748000
	s_nop 0
	v_addc_co_u32_e32 v9, vcc, 0, v7, vcc
	v_lshl_add_u64 v[10:11], s[58:59], 0, v[4:5]
	s_addc_u32 s61, s7, 0
	v_add_co_u32_e32 v12, vcc, s2, v10
	v_lshl_add_u64 v[4:5], s[60:61], 0, v[4:5]
	s_nop 0
	v_addc_co_u32_e32 v13, vcc, 0, v11, vcc
	global_load_dwordx2 v[68:69], v[6:7], off
	global_load_dwordx2 v[66:67], v[8:9], off
	global_load_dwordx2 v[64:65], v[10:11], off
	global_load_dwordx2 v[62:63], v[12:13], off
	v_add_co_u32_e32 v6, vcc, s2, v4
	v_lshl_add_u64 v[2:3], v[2:3], 2, s[50:51]
	s_nop 0
	v_addc_co_u32_e32 v7, vcc, 0, v5, vcc
	s_mov_b32 s8, 0x10000
	global_load_dwordx2 v[80:81], v[4:5], off
	global_load_dwordx2 v[78:79], v[6:7], off
	v_add_co_u32_e32 v4, vcc, s8, v2
	s_add_u32 s8, s6, 0x10548000
	s_nop 0
	v_addc_co_u32_e32 v5, vcc, 0, v3, vcc
	global_load_dwordx4 v[6:9], v[4:5], off
	s_nop 0
	global_load_dwordx4 v[2:5], v[2:3], off
	v_writelane_b32 v254, s8, 18
	s_addc_u32 s8, s7, 0
	v_writelane_b32 v254, s8, 2
	s_add_u32 s8, s6, 0x24ff8000
	v_writelane_b32 v253, s8, 58
	s_addc_u32 s8, s7, 0
	v_writelane_b32 v253, s8, 62
	s_add_u32 s8, s6, 0x12048000
	s_addc_u32 s46, s7, 0
	s_add_u32 s47, s6, 0x273f8000
	v_readlane_b32 s6, v253, 0
	v_writelane_b32 v255, s8, 27
	s_addc_u32 s72, s7, 0
	s_mov_b32 s44, s6
	v_readlane_b32 s73, v253, 17
	s_waitcnt vmcnt(0)
	s_branch .LBB0_636

.LBB0_640:
	v_mov_b32_e32 v86, v201
	s_movk_i32 s6, 0x44
	v_ashrrev_i32_e32 v0, 4, v86
	v_lshlrev_b32_e32 v21, 2, v86
	v_and_b32_e32 v84, 60, v21
	v_mul_lo_u32 v85, v0, s6
	v_add_u32_e32 v10, v85, v84
	v_lshl_add_u32 v10, v10, 2, 0
	s_barrier
	ds_write_b128 v10, v[2:5]
	ds_write_b128 v10, v[6:9] offset:8704
	v_lshlrev_b32_e32 v2, 16, v70
	v_and_b32_e32 v3, 0xffff0000, v70
	v_lshlrev_b32_e32 v4, 16, v71
	v_and_b32_e32 v5, 0xffff0000, v71
	v_lshlrev_b32_e32 v6, 16, v72
	v_and_b32_e32 v7, 0xffff0000, v72
	v_lshlrev_b32_e32 v8, 16, v73
	v_and_b32_e32 v9, 0xffff0000, v73
	v_xor_b32_e32 v3, 0x80000000, v3
	v_xor_b32_e32 v2, 0x80000000, v2
	v_xor_b32_e32 v5, 0x80000000, v5
	v_xor_b32_e32 v4, 0x80000000, v4
	ds_write_b128 v10, v[2:5] offset:17408
	v_xor_b32_e32 v3, 0x80000000, v7
	v_xor_b32_e32 v2, 0x80000000, v6
	v_xor_b32_e32 v5, 0x80000000, v9
	v_xor_b32_e32 v4, 0x80000000, v8
	ds_write_b128 v10, v[2:5] offset:26112
	v_lshlrev_b32_e32 v2, 16, v68
	v_and_b32_e32 v3, 0xffff0000, v68
	v_lshlrev_b32_e32 v4, 16, v69
	v_and_b32_e32 v5, 0xffff0000, v69
	ds_write_b128 v10, v[2:5] offset:34816
	v_lshlrev_b32_e32 v2, 16, v66
	v_and_b32_e32 v3, 0xffff0000, v66
	v_lshlrev_b32_e32 v4, 16, v67
	v_and_b32_e32 v5, 0xffff0000, v67
	ds_write_b128 v10, v[2:5] offset:43520
	v_lshlrev_b32_e32 v2, 16, v60
	v_and_b32_e32 v3, 0xffff0000, v60
	v_lshlrev_b32_e32 v4, 16, v61
	v_and_b32_e32 v5, 0xffff0000, v61
	ds_write_b128 v10, v[2:5] offset:52224
	v_lshlrev_b32_e32 v2, 16, v58
	v_and_b32_e32 v3, 0xffff0000, v58
	v_lshlrev_b32_e32 v4, 16, v59
	v_and_b32_e32 v5, 0xffff0000, v59
	ds_write_b128 v10, v[2:5] offset:60928
	v_lshlrev_b32_e32 v2, 16, v64
	v_and_b32_e32 v3, 0xffff0000, v64
	v_lshlrev_b32_e32 v4, 16, v65
	v_and_b32_e32 v5, 0xffff0000, v65
	v_add_u32_e32 v6, 0x11000, v10
	ds_write_b128 v6, v[2:5]
	v_lshlrev_b32_e32 v2, 16, v62
	v_and_b32_e32 v3, 0xffff0000, v62
	v_lshlrev_b32_e32 v4, 16, v63
	v_and_b32_e32 v5, 0xffff0000, v63
	ds_write_b128 v6, v[2:5] offset:8704
	v_add_u32_e32 v2, s74, v0
	s_and_b32 s75, s8, 7
	v_ashrrev_i32_e32 v3, 31, v2
	v_lshlrev_b64 v[10:11], 9, v[2:3]
	s_lshl_b32 s6, s75, 6
	v_or3_b32 v10, v10, s6, v84
	v_lshl_add_u64 v[2:3], v[10:11], 2, s[50:51]
	s_mov_b32 s6, 0x10000
	v_add_co_u32_e32 v6, vcc, s6, v2
	v_lshlrev_b64 v[10:11], 1, v[10:11]
	s_nop 0
	v_addc_co_u32_e32 v7, vcc, 0, v3, vcc
	v_lshl_add_u64 v[12:13], s[52:53], 0, v[10:11]
	v_add_co_u32_e32 v14, vcc, s2, v12
	v_lshl_add_u64 v[16:17], s[54:55], 0, v[10:11]
	s_nop 0
	v_addc_co_u32_e32 v15, vcc, 0, v13, vcc
	v_add_co_u32_e32 v18, vcc, s2, v16
	s_waitcnt lgkmcnt(0)
	s_barrier
	global_load_dwordx4 v[2:5], v[2:3], off
	s_nop 0
	global_load_dwordx4 v[6:9], v[6:7], off
	v_addc_co_u32_e32 v19, vcc, 0, v17, vcc
	global_load_dwordx2 v[70:71], v[12:13], off
	global_load_dwordx2 v[72:73], v[14:15], off
	global_load_dwordx2 v[68:69], v[16:17], off
	global_load_dwordx2 v[66:67], v[18:19], off
	v_lshl_add_u64 v[12:13], s[56:57], 0, v[10:11]
	v_add_co_u32_e32 v14, vcc, s2, v12
	v_lshl_add_u64 v[16:17], s[58:59], 0, v[10:11]
	s_nop 0
	v_addc_co_u32_e32 v15, vcc, 0, v13, vcc
	v_add_co_u32_e32 v18, vcc, s2, v16
	v_lshl_add_u64 v[10:11], s[60:61], 0, v[10:11]
	s_nop 0
	v_addc_co_u32_e32 v19, vcc, 0, v17, vcc
	global_load_dwordx2 v[60:61], v[12:13], off
	global_load_dwordx2 v[58:59], v[14:15], off
	global_load_dwordx2 v[64:65], v[16:17], off
	global_load_dwordx2 v[62:63], v[18:19], off
	v_add_co_u32_e32 v12, vcc, s2, v10
	v_and_b32_e32 v90, 63, v86
	s_nop 0
	v_addc_co_u32_e32 v13, vcc, 0, v11, vcc
	global_load_dwordx2 v[74:75], v[10:11], off
	global_load_dwordx2 v[76:77], v[12:13], off
	v_ashrrev_i32_e32 v12, 6, v86
	s_movk_i32 s6, 0x880
	v_lshl_add_u32 v0, v90, 2, 0
	v_mul_lo_u32 v10, v12, s6
	v_add_u32_e32 v14, v0, v10
	ds_read2_b32 v[10:11], v14 offset1:68
	ds_read2_b32 v[16:17], v14 offset0:136 offset1:204
	v_add_u32_e32 v13, 0x400, v14
	ds_read2_b32 v[22:23], v13 offset0:16 offset1:84
	ds_read2_b32 v[24:25], v13 offset0:152 offset1:220
	v_add_u32_e32 v21, 0, v21
	s_waitcnt lgkmcnt(3)
	v_mul_f32_e32 v20, v10, v11
	s_waitcnt lgkmcnt(2)
	v_mul_f32_e32 v18, v16, v20
	v_mul_f32_e32 v19, v17, v18
	s_waitcnt lgkmcnt(1)
	v_mul_f32_e32 v16, v22, v19
	v_mul_f32_e32 v17, v23, v16
	s_waitcnt lgkmcnt(0)
	v_mul_f32_e32 v11, v24, v17
	v_mul_f32_e32 v15, v25, v11
	v_add_u32_e32 v21, 0x15400, v21
	ds_write_b32 v21, v15
	v_cmp_lt_i32_e32 vcc, 0, v12
	v_mov_b32_e32 v21, 1.0
	s_waitcnt lgkmcnt(0)
	s_barrier
	s_and_saveexec_b64 s[6:7], vcc
	s_cbranch_execz .LBB0_644
	s_add_i32 s8, 0, 0x15400
	v_lshl_add_u32 v22, v90, 2, s8
	v_mov_b32_e32 v21, 1.0
	s_mov_b64 s[8:9], 0
	v_mov_b32_e32 v23, v12
